# attention permlane row max: one pad state between copies and swaps, dead bpermute index shift removed
# baseline (speedup 1.0000x reference)
; DEVI unsigned pk_bf16(float lo, float hi) { unsigned r; asm("v_cvt_pk_bf16_f32 %0, %1, %2" : "=v"(r) : "v"(lo), "v"(hi)); return r; }
; DEVI bf16x8 mk8(uint2 a, uint2 b) { union { uint4 u; bf16x8 v; } c; c.u = make_uint4(a.x, a.y, b.x, b.y); return c.v; }
; template <int DK, bool BIAS> ...
;     ...
;       for (int qi = 0; qi < 2; ++qi) {
;         float mx = -3e38f;
;         if (BIAS) {
; #pragma unroll
;           for (int kt = 0; kt < 4; ++kt) { const f32x4 nf = *(const f32x4*)(fkm + buf * 64 + 16 * kt + 4 * fq);
; #pragma unroll
;             for (int r = 0; r < 4; ++r) { const float t = fmaf(S[kt][qi][r], sc2, nf[r]); S[kt][qi][r] = t; mx = fmaxf(mx, t); } }
;         } else {
; #pragma unroll
;           for (int kt = 0; kt < 4; ++kt)
; #pragma unroll
;             for (int r = 0; r < 4; ++r) mx = fmaxf(mx, S[kt][qi][r]);
;           mx *= sc2;
;         }
;         mx = fmaxf(mx, __shfl_xor(mx, 16)); mx = fmaxf(mx, __shfl_xor(mx, 32));
;         const float mold = mrun[qi], mnew = fmaxf(mold, mx);
;         mrun[qi] = mnew;
;         float ps = 0.f;
; #pragma unroll
;         for (int kt = 0; kt < 4; ++kt)
; #pragma unroll
;           for (int r = 0; r < 4; ++r) { const float pv = BIAS ? __builtin_amdgcn_exp2f(S[kt][qi][r] - mnew) : __builtin_amdgcn_exp2f(fmaf(S[kt][qi][r], sc2, -mnew)); S[kt][qi][r] = pv; ps += pv; }
;         {
;           const float alpha = __builtin_amdgcn_exp2f(mold - mnew);
;           lrun[qi] *= alpha;
; #pragma unroll
;           for (int et = 0; et < 4; ++et) O[et][qi] *= alpha;
;         }
;         lrun[qi] += ps;
; #pragma unroll
;         for (int k2 = 0; k2 < 2; ++k2) { uint2 lo, hi; lo.x = pk_bf16(S[2 * k2][qi][0], S[2 * k2][qi][1]); lo.y = pk_bf16(S[2 * k2][qi][2], S[2 * k2][qi][3]);
;           hi.x = pk_bf16(S[2 * k2 + 1][qi][0], S[2 * k2 + 1][qi][1]); hi.y = pk_bf16(S[2 * k2 + 1][qi][2], S[2 * k2 + 1][qi][3]); pf[qi][k2] = mk8(lo, hi); }
;       }
; #pragma unroll
;       for (int k2 = 0; k2 < 2; ++k2)
; #pragma unroll
;         for (int et = 0; et < 4; ++et) {
;           const uint2 v0 = *(const uint2*)(Vtm + (buf * 64 + 16 * et + fr) * 72 + 32 * k2 + 4 * fq), v1 = *(const uint2*)(Vtm + (buf * 64 + 16 * et + fr) * 72 + 32 * k2 + 16 + 4 * fq);
;           const bf16x8 va = mk8(v0, v1);
.LBB0_1776:
	s_or_b64 exec, exec, s[18:19]
	ds_read_b128 v[174:177], v168 offset:36864
	ds_read_b128 v[194:197], v168 offset:36928
	ds_read_b128 v[242:245], v168 offset:36992
	ds_read_b128 v[246:249], v168 offset:37056
	s_mov_b32 s100, 0x3e38aa3b
	s_mov_b32 s101, 0x3e38aa3b
	s_waitcnt lgkmcnt(3)
	v_pk_fma_f32 v[210:211], v[80:81], s[100:101], v[174:175]
	v_pk_fma_f32 v[212:213], v[82:83], s[100:101], v[176:177]
	v_pk_fma_f32 v[226:227], v[64:65], s[100:101], v[174:175]
	v_pk_fma_f32 v[228:229], v[66:67], s[100:101], v[176:177]
	s_waitcnt lgkmcnt(2)
	v_pk_fma_f32 v[214:215], v[86:87], s[100:101], v[194:195]
	v_pk_fma_f32 v[216:217], v[88:89], s[100:101], v[196:197]
	v_pk_fma_f32 v[230:231], v[68:69], s[100:101], v[194:195]
	v_pk_fma_f32 v[232:233], v[70:71], s[100:101], v[196:197]
	s_waitcnt lgkmcnt(1)
	v_pk_fma_f32 v[218:219], v[90:91], s[100:101], v[242:243]
	v_pk_fma_f32 v[220:221], v[92:93], s[100:101], v[244:245]
	v_pk_fma_f32 v[234:235], v[72:73], s[100:101], v[242:243]
	v_pk_fma_f32 v[236:237], v[74:75], s[100:101], v[244:245]
	s_waitcnt lgkmcnt(0)
	v_pk_fma_f32 v[222:223], v[94:95], s[100:101], v[246:247]
	v_pk_fma_f32 v[224:225], v[96:97], s[100:101], v[248:249]
	v_pk_fma_f32 v[238:239], v[76:77], s[100:101], v[246:247]
	v_pk_fma_f32 v[240:241], v[78:79], s[100:101], v[248:249]
	v_max3_f32 v84, v210, s31, v211
	v_max3_f32 v85, v226, s31, v227
	v_max3_f32 v84, v84, v212, v213
	v_max3_f32 v85, v85, v228, v229
	v_max3_f32 v84, v84, v214, v215
	v_max3_f32 v85, v85, v230, v231
	v_max3_f32 v84, v84, v216, v217
	v_max3_f32 v85, v85, v232, v233
	v_max3_f32 v84, v84, v218, v219
	v_max3_f32 v85, v85, v234, v235
	v_max3_f32 v84, v84, v220, v221
	v_max3_f32 v85, v85, v236, v237
	v_max3_f32 v84, v84, v222, v223
	v_max3_f32 v85, v85, v238, v239
	v_max3_f32 v84, v84, v224, v225
	v_max3_f32 v85, v85, v240, v241
	v_mov_b32_e32 v86, v84
	v_mov_b32_e32 v87, v85
	s_nop 0
	v_permlane16_swap_b32_e32 v86, v84
	v_permlane16_swap_b32_e32 v87, v85
	v_max_f32_e32 v84, v84, v86
	v_max_f32_e32 v85, v85, v87
	v_mov_b32_e32 v86, v84
	v_mov_b32_e32 v87, v85
	s_nop 0
	v_permlane32_swap_b32_e32 v86, v84
	v_permlane32_swap_b32_e32 v87, v85
	v_max3_f32 v131, v114, v84, v86
	v_max3_f32 v173, v112, v85, v87
	v_sub_f32_e32 v84, v114, v131
	v_sub_f32_e32 v85, v112, v173
	v_exp_f32_e32 v126, v84
	v_exp_f32_e32 v82, v85
	v_sub_f32_e32 v86, 0, v131
	v_sub_f32_e32 v80, 0, v173
	v_pk_add_f32 v[210:211], v[210:211], v[86:87] op_sel_hi:[1,0]
	v_pk_add_f32 v[212:213], v[212:213], v[86:87] op_sel_hi:[1,0]
	v_pk_add_f32 v[226:227], v[226:227], v[80:81] op_sel_hi:[1,0]
	v_pk_add_f32 v[228:229], v[228:229], v[80:81] op_sel_hi:[1,0]
	v_pk_add_f32 v[214:215], v[214:215], v[86:87] op_sel_hi:[1,0]
	v_pk_add_f32 v[216:217], v[216:217], v[86:87] op_sel_hi:[1,0]
	v_pk_add_f32 v[230:231], v[230:231], v[80:81] op_sel_hi:[1,0]
	v_pk_add_f32 v[232:233], v[232:233], v[80:81] op_sel_hi:[1,0]
	v_pk_add_f32 v[218:219], v[218:219], v[86:87] op_sel_hi:[1,0]
	v_pk_add_f32 v[220:221], v[220:221], v[86:87] op_sel_hi:[1,0]
	v_pk_add_f32 v[234:235], v[234:235], v[80:81] op_sel_hi:[1,0]
	v_pk_add_f32 v[236:237], v[236:237], v[80:81] op_sel_hi:[1,0]
	v_pk_add_f32 v[222:223], v[222:223], v[86:87] op_sel_hi:[1,0]
	v_pk_add_f32 v[224:225], v[224:225], v[86:87] op_sel_hi:[1,0]
	v_pk_add_f32 v[238:239], v[238:239], v[80:81] op_sel_hi:[1,0]
	v_pk_add_f32 v[240:241], v[240:241], v[80:81] op_sel_hi:[1,0]
	v_exp_f32_e32 v155, v210
	v_exp_f32_e32 v154, v226
	v_exp_f32_e32 v157, v211
	v_exp_f32_e32 v156, v227
	v_exp_f32_e32 v151, v212
	v_exp_f32_e32 v150, v228
	v_exp_f32_e32 v153, v213
	v_exp_f32_e32 v152, v229
	v_exp_f32_e32 v117, v214
	v_exp_f32_e32 v116, v230
	v_exp_f32_e32 v119, v215
	v_exp_f32_e32 v118, v231
	v_exp_f32_e32 v123, v216
	v_exp_f32_e32 v122, v232
	v_exp_f32_e32 v121, v217
	v_exp_f32_e32 v120, v233
	v_exp_f32_e32 v125, v218
	v_exp_f32_e32 v124, v234
	v_exp_f32_e32 v89, v219
	v_exp_f32_e32 v88, v235
	v_exp_f32_e32 v95, v220
	v_exp_f32_e32 v94, v236
	v_exp_f32_e32 v115, v221
	v_exp_f32_e32 v114, v237
	v_exp_f32_e32 v93, v222
	v_exp_f32_e32 v92, v238
	v_exp_f32_e32 v113, v223
	v_exp_f32_e32 v112, v239
	v_exp_f32_e32 v91, v224
	v_exp_f32_e32 v90, v240
	v_exp_f32_e32 v97, v225
	v_exp_f32_e32 v96, v241
	v_add_u32_e32 v242, 0x4800, v170
	v_add_u32_e32 v243, 0x5000, v170
	v_add_u32_e32 v244, 0x5800, v170
	v_add_u32_e32 v245, 0x6000, v170
	ds_read2_b64 v[210:213], v242 offset1:4
	ds_read2_b64 v[214:217], v243 offset0:32 offset1:36
	ds_read2_b64 v[218:221], v244 offset0:64 offset1:68
	ds_read2_b64 v[222:225], v245 offset0:96 offset1:100
	ds_read2_b64 v[226:229], v242 offset0:8 offset1:12
	ds_read2_b64 v[230:233], v243 offset0:40 offset1:44
	ds_read2_b64 v[234:237], v244 offset0:72 offset1:76
	ds_read2_b64 v[238:241], v245 offset0:104 offset1:108
	v_pk_mul_f32 v[202:203], v[52:53], v[126:127] op_sel_hi:[1,0]
	v_pk_mul_f32 v[52:53], v[56:57], v[126:127] op_sel_hi:[1,0]
	v_pk_mul_f32 v[198:199], v[48:49], v[126:127] op_sel_hi:[1,0]
	v_pk_mul_f32 v[48:49], v[60:61], v[126:127] op_sel_hi:[1,0]
	v_pk_mul_f32 v[200:201], v[50:51], v[126:127] op_sel_hi:[1,0]
	v_pk_mul_f32 v[204:205], v[54:55], v[126:127] op_sel_hi:[1,0]
	v_pk_add_f32 v[64:65], v[154:155], 0 op_sel_hi:[1,0]
	v_pk_add_f32 v[80:81], v[156:157], v[64:65]
	v_pk_mul_f32 v[46:47], v[46:47], v[82:83] op_sel_hi:[1,0]
	v_pk_mul_f32 v[44:45], v[44:45], v[82:83] op_sel_hi:[1,0]
	v_pk_mul_f32 v[54:55], v[58:59], v[126:127] op_sel_hi:[1,0]
	v_cvt_pk_bf16_f32 v56, v155, v157
	v_cvt_pk_bf16_f32 v57, v151, v153
	v_cvt_pk_bf16_f32 v58, v117, v119
	v_cvt_pk_bf16_f32 v59, v123, v121
	v_cvt_pk_bf16_f32 v68, v154, v156
	s_waitcnt lgkmcnt(7)
; DEVI unsigned pk_bf16(float lo, float hi) { unsigned r; asm("v_cvt_pk_bf16_f32 %0, %1, %2" : "=v"(r) : "v"(lo), "v"(hi)); return r; }
; DEVI bf16x8 mk8(uint2 a, uint2 b) { union { uint4 u; bf16x8 v; } c; c.u = make_uint4(a.x, a.y, b.x, b.y); return c.v; }
; #define MFMA(a, b, c) __builtin_amdgcn_mfma_f32_16x16x32_bf16((a), (b), (c), 0, 0, 0)
; template <int DK, bool BIAS> ...
;     ...
;         {
;           const float alpha = __builtin_amdgcn_exp2f(mold - mnew);
;           lrun[qi] *= alpha;
; #pragma unroll
;           for (int et = 0; et < 4; ++et) O[et][qi] *= alpha;
;         }
;         lrun[qi] += ps;
; #pragma unroll
;         for (int k2 = 0; k2 < 2; ++k2) { uint2 lo, hi; lo.x = pk_bf16(S[2 * k2][qi][0], S[2 * k2][qi][1]); lo.y = pk_bf16(S[2 * k2][qi][2], S[2 * k2][qi][3]);
;           hi.x = pk_bf16(S[2 * k2 + 1][qi][0], S[2 * k2 + 1][qi][1]); hi.y = pk_bf16(S[2 * k2 + 1][qi][2], S[2 * k2 + 1][qi][3]); pf[qi][k2] = mk8(lo, hi); }
;       }
; #pragma unroll
;       for (int k2 = 0; k2 < 2; ++k2)
; #pragma unroll
;         for (int et = 0; et < 4; ++et) {
;           const uint2 v0 = *(const uint2*)(Vtm + (buf * 64 + 16 * et + fr) * 72 + 32 * k2 + 4 * fq), v1 = *(const uint2*)(Vtm + (buf * 64 + 16 * et + fr) * 72 + 32 * k2 + 16 + 4 * fq);
;           const bf16x8 va = mk8(v0, v1);
; #pragma unroll
;           for (int qi = 0; qi < 2; ++qi) O[et][qi] = MFMA(va, pf[qi][k2], O[et][qi]);
;         }
	v_mfma_f32_16x16x32_bf16 v[76:79], v[210:213], v[56:59], v[198:201]
	v_cvt_pk_bf16_f32 v69, v150, v152
	v_cvt_pk_bf16_f32 v70, v116, v118
	v_cvt_pk_bf16_f32 v71, v122, v120
	v_pk_mul_f32 v[42:43], v[42:43], v[82:83] op_sel_hi:[1,0]
	s_nop 0
	v_mfma_f32_16x16x32_bf16 v[44:47], v[210:213], v[68:71], v[44:47]
	v_pk_mul_f32 v[40:41], v[40:41], v[82:83] op_sel_hi:[1,0]
	s_waitcnt lgkmcnt(6)
	v_mfma_f32_16x16x32_bf16 v[84:87], v[214:217], v[56:59], v[202:205]
	v_pk_mul_f32 v[50:51], v[62:63], v[126:127] op_sel_hi:[1,0]
	v_mfma_f32_16x16x32_bf16 v[40:43], v[214:217], v[68:71], v[40:43]
	v_pk_mul_f32 v[38:39], v[38:39], v[82:83] op_sel_hi:[1,0]
	v_pk_mul_f32 v[36:37], v[36:37], v[82:83] op_sel_hi:[1,0]
	s_waitcnt lgkmcnt(5)
	v_mfma_f32_16x16x32_bf16 v[154:157], v[218:221], v[56:59], v[52:55]
	v_pk_mul_f32 v[34:35], v[34:35], v[82:83] op_sel_hi:[1,0]
	v_pk_mul_f32 v[32:33], v[32:33], v[82:83] op_sel_hi:[1,0]
	v_cvt_pk_bf16_f32 v60, v125, v89
	v_mfma_f32_16x16x32_bf16 v[36:39], v[218:221], v[68:71], v[36:39]
	s_waitcnt lgkmcnt(4)
	v_mfma_f32_16x16x32_bf16 v[64:67], v[222:225], v[56:59], v[48:51]
	v_cvt_pk_bf16_f32 v61, v95, v115
	v_cvt_pk_bf16_f32 v62, v93, v113
	v_cvt_pk_bf16_f32 v63, v91, v97
	s_nop 0
	v_mfma_f32_16x16x32_bf16 v[32:35], v[222:225], v[68:71], v[32:35]
	v_cvt_pk_bf16_f32 v68, v124, v88
	v_cvt_pk_bf16_f32 v69, v94, v114
	s_waitcnt lgkmcnt(3)
	v_mfma_f32_16x16x32_bf16 v[48:51], v[226:229], v[60:63], v[76:79]
	v_cvt_pk_bf16_f32 v70, v92, v112
	v_cvt_pk_bf16_f32 v71, v90, v96
	s_nop 1
	v_mfma_f32_16x16x32_bf16 v[44:47], v[226:229], v[68:71], v[44:47]
	v_pk_add_f32 v[52:53], v[150:151], v[80:81]
	v_mov_b32_e32 v83, v126
	v_pk_add_f32 v[76:77], v[152:153], v[52:53]
	s_waitcnt lgkmcnt(2)
	v_mfma_f32_16x16x32_bf16 v[52:55], v[230:233], v[60:63], v[84:87]
	v_pk_add_f32 v[76:77], v[116:117], v[76:77]
	v_pk_add_f32 v[76:77], v[118:119], v[76:77]
	v_mfma_f32_16x16x32_bf16 v[40:43], v[230:233], v[68:71], v[40:43]
	v_pk_add_f32 v[76:77], v[122:123], v[76:77]
	v_pk_add_f32 v[56:57], v[120:121], v[76:77]
	v_pk_add_f32 v[80:81], v[124:125], v[56:57]
	s_waitcnt lgkmcnt(1)
	v_mfma_f32_16x16x32_bf16 v[56:59], v[234:237], v[60:63], v[154:157]
	v_pk_add_f32 v[80:81], v[88:89], v[80:81]
	v_pk_add_f32 v[80:81], v[94:95], v[80:81]
	v_mfma_f32_16x16x32_bf16 v[36:39], v[234:237], v[68:71], v[36:39]
	v_pk_add_f32 v[80:81], v[114:115], v[80:81]
	v_mov_b32_e32 v114, v131
	v_pk_add_f32 v[72:73], v[92:93], v[80:81]
	s_waitcnt lgkmcnt(0)
	v_mfma_f32_16x16x32_bf16 v[60:63], v[238:241], v[60:63], v[64:67]
	v_pk_add_f32 v[72:73], v[112:113], v[72:73]
	v_mov_b32_e32 v112, v173
	v_mfma_f32_16x16x32_bf16 v[32:35], v[238:241], v[68:71], v[32:35]
	v_pk_add_f32 v[64:65], v[90:91], v[72:73]
	v_pk_add_f32 v[64:65], v[96:97], v[64:65]
	s_nop 0
	v_pk_fma_f32 v[106:107], v[106:107], v[82:83], v[64:65]

; DEVI unsigned pk_bf16(float lo, float hi) { unsigned r; asm("v_cvt_pk_bf16_f32 %0, %1, %2" : "=v"(r) : "v"(lo), "v"(hi)); return r; }
; DEVI bf16x8 mk8(uint2 a, uint2 b) { union { uint4 u; bf16x8 v; } c; c.u = make_uint4(a.x, a.y, b.x, b.y); return c.v; }
; template <int DK, bool BIAS> ...
;     ...
;       for (int qi = 0; qi < 2; ++qi) {
;         float mx = -3e38f;
;         if (BIAS) {
; #pragma unroll
;           for (int kt = 0; kt < 4; ++kt) { const f32x4 nf = *(const f32x4*)(fkm + buf * 64 + 16 * kt + 4 * fq);
; #pragma unroll
;             for (int r = 0; r < 4; ++r) { const float t = fmaf(S[kt][qi][r], sc2, nf[r]); S[kt][qi][r] = t; mx = fmaxf(mx, t); } }
;         } else {
; #pragma unroll
;           for (int kt = 0; kt < 4; ++kt)
; #pragma unroll
;             for (int r = 0; r < 4; ++r) mx = fmaxf(mx, S[kt][qi][r]);
;           mx *= sc2;
;         }
;         mx = fmaxf(mx, __shfl_xor(mx, 16)); mx = fmaxf(mx, __shfl_xor(mx, 32));
;         const float mold = mrun[qi], mnew = fmaxf(mold, mx);
;         mrun[qi] = mnew;
;         float ps = 0.f;
; #pragma unroll
;         for (int kt = 0; kt < 4; ++kt)
; #pragma unroll
;           for (int r = 0; r < 4; ++r) { const float pv = BIAS ? __builtin_amdgcn_exp2f(S[kt][qi][r] - mnew) : __builtin_amdgcn_exp2f(fmaf(S[kt][qi][r], sc2, -mnew)); S[kt][qi][r] = pv; ps += pv; }
;         {
;           const float alpha = __builtin_amdgcn_exp2f(mold - mnew);
;           lrun[qi] *= alpha;
; #pragma unroll
;           for (int et = 0; et < 4; ++et) O[et][qi] *= alpha;
;         }
;         lrun[qi] += ps;
; #pragma unroll
;         for (int k2 = 0; k2 < 2; ++k2) { uint2 lo, hi; lo.x = pk_bf16(S[2 * k2][qi][0], S[2 * k2][qi][1]); lo.y = pk_bf16(S[2 * k2][qi][2], S[2 * k2][qi][3]);
;           hi.x = pk_bf16(S[2 * k2 + 1][qi][0], S[2 * k2 + 1][qi][1]); hi.y = pk_bf16(S[2 * k2 + 1][qi][2], S[2 * k2 + 1][qi][3]); pf[qi][k2] = mk8(lo, hi); }
;       }
; #pragma unroll
;       for (int k2 = 0; k2 < 2; ++k2)
; #pragma unroll
;         for (int et = 0; et < 4; ++et) {
;           const uint2 v0 = *(const uint2*)(Vtm + (buf * 64 + 16 * et + fr) * 72 + 32 * k2 + 4 * fq), v1 = *(const uint2*)(Vtm + (buf * 64 + 16 * et + fr) * 72 + 32 * k2 + 16 + 4 * fq);
;           const bf16x8 va = mk8(v0, v1);
.LBB0_1797:
	s_or_b64 exec, exec, s[18:19]
	ds_read_b128 v[174:177], v104 offset:37120
	ds_read_b128 v[194:197], v104 offset:37184
	ds_read_b128 v[242:245], v104 offset:37248
	ds_read_b128 v[246:249], v104 offset:37312
	s_mov_b32 s100, 0x3e38aa3b
	s_mov_b32 s101, 0x3e38aa3b
	s_waitcnt lgkmcnt(3)
	v_pk_fma_f32 v[210:211], v[80:81], s[100:101], v[174:175]
	v_pk_fma_f32 v[212:213], v[82:83], s[100:101], v[176:177]
	v_pk_fma_f32 v[226:227], v[64:65], s[100:101], v[174:175]
	v_pk_fma_f32 v[228:229], v[66:67], s[100:101], v[176:177]
	s_waitcnt lgkmcnt(2)
	v_pk_fma_f32 v[214:215], v[86:87], s[100:101], v[194:195]
	v_pk_fma_f32 v[216:217], v[88:89], s[100:101], v[196:197]
	v_pk_fma_f32 v[230:231], v[68:69], s[100:101], v[194:195]
	v_pk_fma_f32 v[232:233], v[70:71], s[100:101], v[196:197]
	s_waitcnt lgkmcnt(1)
	v_pk_fma_f32 v[218:219], v[90:91], s[100:101], v[242:243]
	v_pk_fma_f32 v[220:221], v[92:93], s[100:101], v[244:245]
	v_pk_fma_f32 v[234:235], v[72:73], s[100:101], v[242:243]
	v_pk_fma_f32 v[236:237], v[74:75], s[100:101], v[244:245]
	s_waitcnt lgkmcnt(0)
	v_pk_fma_f32 v[222:223], v[94:95], s[100:101], v[246:247]
	v_pk_fma_f32 v[224:225], v[96:97], s[100:101], v[248:249]
	v_pk_fma_f32 v[238:239], v[76:77], s[100:101], v[246:247]
	v_pk_fma_f32 v[240:241], v[78:79], s[100:101], v[248:249]
	v_max3_f32 v84, v210, s31, v211
	v_max3_f32 v85, v226, s31, v227
	v_max3_f32 v84, v84, v212, v213
	v_max3_f32 v85, v85, v228, v229
	v_max3_f32 v84, v84, v214, v215
	v_max3_f32 v85, v85, v230, v231
	v_max3_f32 v84, v84, v216, v217
	v_max3_f32 v85, v85, v232, v233
	v_max3_f32 v84, v84, v218, v219
	v_max3_f32 v85, v85, v234, v235
	v_max3_f32 v84, v84, v220, v221
	v_max3_f32 v85, v85, v236, v237
	v_max3_f32 v84, v84, v222, v223
	v_max3_f32 v85, v85, v238, v239
	v_max3_f32 v84, v84, v224, v225
	v_max3_f32 v85, v85, v240, v241
	v_mov_b32_e32 v86, v84
	v_mov_b32_e32 v87, v85
	s_nop 0
	v_permlane16_swap_b32_e32 v86, v84
	v_permlane16_swap_b32_e32 v87, v85
	v_max_f32_e32 v84, v84, v86
	v_max_f32_e32 v85, v85, v87
	v_mov_b32_e32 v86, v84
	v_mov_b32_e32 v87, v85
	s_nop 0
	v_permlane32_swap_b32_e32 v86, v84
	v_permlane32_swap_b32_e32 v87, v85
	v_max3_f32 v131, v114, v84, v86
	v_max3_f32 v173, v112, v85, v87
	v_sub_f32_e32 v84, v114, v131
	v_sub_f32_e32 v85, v112, v173
	v_exp_f32_e32 v126, v84
	v_exp_f32_e32 v82, v85
	v_sub_f32_e32 v86, 0, v131
	v_sub_f32_e32 v80, 0, v173
	v_pk_add_f32 v[210:211], v[210:211], v[86:87] op_sel_hi:[1,0]
	v_pk_add_f32 v[212:213], v[212:213], v[86:87] op_sel_hi:[1,0]
	v_pk_add_f32 v[226:227], v[226:227], v[80:81] op_sel_hi:[1,0]
	v_pk_add_f32 v[228:229], v[228:229], v[80:81] op_sel_hi:[1,0]
	v_pk_add_f32 v[214:215], v[214:215], v[86:87] op_sel_hi:[1,0]
	v_pk_add_f32 v[216:217], v[216:217], v[86:87] op_sel_hi:[1,0]
	v_pk_add_f32 v[230:231], v[230:231], v[80:81] op_sel_hi:[1,0]
	v_pk_add_f32 v[232:233], v[232:233], v[80:81] op_sel_hi:[1,0]
	v_pk_add_f32 v[218:219], v[218:219], v[86:87] op_sel_hi:[1,0]
	v_pk_add_f32 v[220:221], v[220:221], v[86:87] op_sel_hi:[1,0]
	v_pk_add_f32 v[234:235], v[234:235], v[80:81] op_sel_hi:[1,0]
	v_pk_add_f32 v[236:237], v[236:237], v[80:81] op_sel_hi:[1,0]
	v_pk_add_f32 v[222:223], v[222:223], v[86:87] op_sel_hi:[1,0]
	v_pk_add_f32 v[224:225], v[224:225], v[86:87] op_sel_hi:[1,0]
	v_pk_add_f32 v[238:239], v[238:239], v[80:81] op_sel_hi:[1,0]
	v_pk_add_f32 v[240:241], v[240:241], v[80:81] op_sel_hi:[1,0]
	v_exp_f32_e32 v155, v210
	v_exp_f32_e32 v154, v226
	v_exp_f32_e32 v157, v211
	v_exp_f32_e32 v156, v227
	v_exp_f32_e32 v151, v212
	v_exp_f32_e32 v150, v228
	v_exp_f32_e32 v153, v213
	v_exp_f32_e32 v152, v229
	v_exp_f32_e32 v117, v214
	v_exp_f32_e32 v116, v230
	v_exp_f32_e32 v119, v215
	v_exp_f32_e32 v118, v231
	v_exp_f32_e32 v123, v216
	v_exp_f32_e32 v122, v232
	v_exp_f32_e32 v121, v217
	v_exp_f32_e32 v120, v233
	v_exp_f32_e32 v125, v218
	v_exp_f32_e32 v124, v234
	v_exp_f32_e32 v89, v219
	v_exp_f32_e32 v88, v235
	v_exp_f32_e32 v95, v220
	v_exp_f32_e32 v94, v236
	v_exp_f32_e32 v115, v221
	v_exp_f32_e32 v114, v237
	v_exp_f32_e32 v93, v222
	v_exp_f32_e32 v92, v238
	v_exp_f32_e32 v113, v223
	v_exp_f32_e32 v112, v239
	v_exp_f32_e32 v91, v224
	v_exp_f32_e32 v90, v240
	v_exp_f32_e32 v97, v225
	v_exp_f32_e32 v96, v241
	v_add_u32_e32 v242, 0x6800, v170
	v_add_u32_e32 v243, 0x7000, v170
	v_add_u32_e32 v244, 0x7800, v170
	v_add_u32_e32 v245, 0x8000, v170
	ds_read2_b64 v[210:213], v242 offset0:128 offset1:132
	ds_read2_b64 v[214:217], v243 offset0:160 offset1:164
	ds_read2_b64 v[218:221], v244 offset0:192 offset1:196
	ds_read2_b64 v[222:225], v245 offset0:224 offset1:228
	ds_read2_b64 v[226:229], v242 offset0:136 offset1:140
	ds_read2_b64 v[230:233], v243 offset0:168 offset1:172
	ds_read2_b64 v[234:237], v244 offset0:200 offset1:204
	ds_read2_b64 v[238:241], v245 offset0:232 offset1:236
	v_pk_mul_f32 v[202:203], v[52:53], v[126:127] op_sel_hi:[1,0]
	v_pk_mul_f32 v[52:53], v[56:57], v[126:127] op_sel_hi:[1,0]
	v_pk_mul_f32 v[198:199], v[48:49], v[126:127] op_sel_hi:[1,0]
	v_pk_mul_f32 v[48:49], v[60:61], v[126:127] op_sel_hi:[1,0]
	v_pk_mul_f32 v[200:201], v[50:51], v[126:127] op_sel_hi:[1,0]
	v_pk_mul_f32 v[204:205], v[54:55], v[126:127] op_sel_hi:[1,0]
	v_pk_add_f32 v[64:65], v[154:155], 0 op_sel_hi:[1,0]
	v_pk_add_f32 v[80:81], v[156:157], v[64:65]
	v_pk_mul_f32 v[46:47], v[46:47], v[82:83] op_sel_hi:[1,0]
	v_pk_mul_f32 v[44:45], v[44:45], v[82:83] op_sel_hi:[1,0]
	v_pk_mul_f32 v[54:55], v[58:59], v[126:127] op_sel_hi:[1,0]
	v_cvt_pk_bf16_f32 v56, v155, v157
	v_cvt_pk_bf16_f32 v57, v151, v153
	v_cvt_pk_bf16_f32 v58, v117, v119
	v_cvt_pk_bf16_f32 v59, v123, v121
	v_cvt_pk_bf16_f32 v68, v154, v156
	s_waitcnt lgkmcnt(7)
; DEVI unsigned pk_bf16(float lo, float hi) { unsigned r; asm("v_cvt_pk_bf16_f32 %0, %1, %2" : "=v"(r) : "v"(lo), "v"(hi)); return r; }
; DEVI bf16x8 mk8(uint2 a, uint2 b) { union { uint4 u; bf16x8 v; } c; c.u = make_uint4(a.x, a.y, b.x, b.y); return c.v; }
; #define MFMA(a, b, c) __builtin_amdgcn_mfma_f32_16x16x32_bf16((a), (b), (c), 0, 0, 0)
; template <int DK, bool BIAS> ...
;     ...
;         {
;           const float alpha = __builtin_amdgcn_exp2f(mold - mnew);
;           lrun[qi] *= alpha;
; #pragma unroll
;           for (int et = 0; et < 4; ++et) O[et][qi] *= alpha;
;         }
;         lrun[qi] += ps;
; #pragma unroll
;         for (int k2 = 0; k2 < 2; ++k2) { uint2 lo, hi; lo.x = pk_bf16(S[2 * k2][qi][0], S[2 * k2][qi][1]); lo.y = pk_bf16(S[2 * k2][qi][2], S[2 * k2][qi][3]);
;           hi.x = pk_bf16(S[2 * k2 + 1][qi][0], S[2 * k2 + 1][qi][1]); hi.y = pk_bf16(S[2 * k2 + 1][qi][2], S[2 * k2 + 1][qi][3]); pf[qi][k2] = mk8(lo, hi); }
;       }
; #pragma unroll
;       for (int k2 = 0; k2 < 2; ++k2)
; #pragma unroll
;         for (int et = 0; et < 4; ++et) {
;           const uint2 v0 = *(const uint2*)(Vtm + (buf * 64 + 16 * et + fr) * 72 + 32 * k2 + 4 * fq), v1 = *(const uint2*)(Vtm + (buf * 64 + 16 * et + fr) * 72 + 32 * k2 + 16 + 4 * fq);
;           const bf16x8 va = mk8(v0, v1);
; #pragma unroll
;           for (int qi = 0; qi < 2; ++qi) O[et][qi] = MFMA(va, pf[qi][k2], O[et][qi]);
;         }
	v_mfma_f32_16x16x32_bf16 v[76:79], v[210:213], v[56:59], v[198:201]
	v_cvt_pk_bf16_f32 v69, v150, v152
	v_cvt_pk_bf16_f32 v70, v116, v118
	v_cvt_pk_bf16_f32 v71, v122, v120
	v_pk_mul_f32 v[42:43], v[42:43], v[82:83] op_sel_hi:[1,0]
	s_nop 0
	v_mfma_f32_16x16x32_bf16 v[44:47], v[210:213], v[68:71], v[44:47]
	v_pk_mul_f32 v[40:41], v[40:41], v[82:83] op_sel_hi:[1,0]
	s_waitcnt lgkmcnt(6)
	v_mfma_f32_16x16x32_bf16 v[84:87], v[214:217], v[56:59], v[202:205]
	v_pk_mul_f32 v[50:51], v[62:63], v[126:127] op_sel_hi:[1,0]
	v_mfma_f32_16x16x32_bf16 v[40:43], v[214:217], v[68:71], v[40:43]
	v_pk_mul_f32 v[38:39], v[38:39], v[82:83] op_sel_hi:[1,0]
	v_pk_mul_f32 v[36:37], v[36:37], v[82:83] op_sel_hi:[1,0]
	s_waitcnt lgkmcnt(5)
	v_mfma_f32_16x16x32_bf16 v[154:157], v[218:221], v[56:59], v[52:55]
	v_pk_mul_f32 v[34:35], v[34:35], v[82:83] op_sel_hi:[1,0]
	v_pk_mul_f32 v[32:33], v[32:33], v[82:83] op_sel_hi:[1,0]
	v_cvt_pk_bf16_f32 v60, v125, v89
	v_mfma_f32_16x16x32_bf16 v[36:39], v[218:221], v[68:71], v[36:39]
	s_waitcnt lgkmcnt(4)
	v_mfma_f32_16x16x32_bf16 v[64:67], v[222:225], v[56:59], v[48:51]
	v_cvt_pk_bf16_f32 v61, v95, v115
	v_cvt_pk_bf16_f32 v62, v93, v113
	v_cvt_pk_bf16_f32 v63, v91, v97
	s_nop 0
	v_mfma_f32_16x16x32_bf16 v[32:35], v[222:225], v[68:71], v[32:35]
	v_cvt_pk_bf16_f32 v68, v124, v88
	v_cvt_pk_bf16_f32 v69, v94, v114
	s_waitcnt lgkmcnt(3)
	v_mfma_f32_16x16x32_bf16 v[48:51], v[226:229], v[60:63], v[76:79]
	v_cvt_pk_bf16_f32 v70, v92, v112
	v_cvt_pk_bf16_f32 v71, v90, v96
	s_nop 1
	v_mfma_f32_16x16x32_bf16 v[44:47], v[226:229], v[68:71], v[44:47]
	v_pk_add_f32 v[52:53], v[150:151], v[80:81]
	v_mov_b32_e32 v83, v126
	v_pk_add_f32 v[76:77], v[152:153], v[52:53]
	s_waitcnt lgkmcnt(2)
	v_mfma_f32_16x16x32_bf16 v[52:55], v[230:233], v[60:63], v[84:87]
	v_pk_add_f32 v[76:77], v[116:117], v[76:77]
	v_pk_add_f32 v[76:77], v[118:119], v[76:77]
	v_mfma_f32_16x16x32_bf16 v[40:43], v[230:233], v[68:71], v[40:43]
	v_pk_add_f32 v[76:77], v[122:123], v[76:77]
	v_pk_add_f32 v[56:57], v[120:121], v[76:77]
	v_pk_add_f32 v[80:81], v[124:125], v[56:57]
	s_waitcnt lgkmcnt(1)
	v_mfma_f32_16x16x32_bf16 v[56:59], v[234:237], v[60:63], v[154:157]
	v_pk_add_f32 v[80:81], v[88:89], v[80:81]
	v_pk_add_f32 v[80:81], v[94:95], v[80:81]
	v_mfma_f32_16x16x32_bf16 v[36:39], v[234:237], v[68:71], v[36:39]
	v_pk_add_f32 v[80:81], v[114:115], v[80:81]
	v_mov_b32_e32 v114, v131
	v_pk_add_f32 v[72:73], v[92:93], v[80:81]
	s_waitcnt lgkmcnt(0)
	v_mfma_f32_16x16x32_bf16 v[60:63], v[238:241], v[60:63], v[64:67]
	v_pk_add_f32 v[72:73], v[112:113], v[72:73]
	v_mov_b32_e32 v112, v173
	v_mfma_f32_16x16x32_bf16 v[32:35], v[238:241], v[68:71], v[32:35]
	v_pk_add_f32 v[64:65], v[90:91], v[72:73]
	v_pk_add_f32 v[64:65], v[96:97], v[64:65]
	s_nop 0
	v_pk_fma_f32 v[106:107], v[106:107], v[82:83], v[64:65]

; DEVI unsigned pk_bf16(float lo, float hi) { unsigned r; asm("v_cvt_pk_bf16_f32 %0, %1, %2" : "=v"(r) : "v"(lo), "v"(hi)); return r; }
; DEVI bf16x8 mk8(uint2 a, uint2 b) { union { uint4 u; bf16x8 v; } c; c.u = make_uint4(a.x, a.y, b.x, b.y); return c.v; }
; template <int DK, bool BIAS> ...
;     ...
;       for (int qi = 0; qi < 2; ++qi) {
;         float mx = -3e38f;
;         if (BIAS) {
; #pragma unroll
;           for (int kt = 0; kt < 4; ++kt) { const f32x4 nf = *(const f32x4*)(fkm + buf * 64 + 16 * kt + 4 * fq);
; #pragma unroll
;             for (int r = 0; r < 4; ++r) { const float t = fmaf(S[kt][qi][r], sc2, nf[r]); S[kt][qi][r] = t; mx = fmaxf(mx, t); } }
;         } else {
; #pragma unroll
;           for (int kt = 0; kt < 4; ++kt)
; #pragma unroll
;             for (int r = 0; r < 4; ++r) mx = fmaxf(mx, S[kt][qi][r]);
;           mx *= sc2;
;         }
;         mx = fmaxf(mx, __shfl_xor(mx, 16)); mx = fmaxf(mx, __shfl_xor(mx, 32));
;         const float mold = mrun[qi], mnew = fmaxf(mold, mx);
;         mrun[qi] = mnew;
;         float ps = 0.f;
; #pragma unroll
;         for (int kt = 0; kt < 4; ++kt)
; #pragma unroll
;           for (int r = 0; r < 4; ++r) { const float pv = BIAS ? __builtin_amdgcn_exp2f(S[kt][qi][r] - mnew) : __builtin_amdgcn_exp2f(fmaf(S[kt][qi][r], sc2, -mnew)); S[kt][qi][r] = pv; ps += pv; }
;         {
;           const float alpha = __builtin_amdgcn_exp2f(mold - mnew);
;           lrun[qi] *= alpha;
; #pragma unroll
;           for (int et = 0; et < 4; ++et) O[et][qi] *= alpha;
;         }
;         lrun[qi] += ps;
; #pragma unroll
;         for (int k2 = 0; k2 < 2; ++k2) { uint2 lo, hi; lo.x = pk_bf16(S[2 * k2][qi][0], S[2 * k2][qi][1]); lo.y = pk_bf16(S[2 * k2][qi][2], S[2 * k2][qi][3]);
;           hi.x = pk_bf16(S[2 * k2 + 1][qi][0], S[2 * k2 + 1][qi][1]); hi.y = pk_bf16(S[2 * k2 + 1][qi][2], S[2 * k2 + 1][qi][3]); pf[qi][k2] = mk8(lo, hi); }
;       }
; #pragma unroll
;       for (int k2 = 0; k2 < 2; ++k2)
; #pragma unroll
;         for (int et = 0; et < 4; ++et) {
;           const uint2 v0 = *(const uint2*)(Vtm + (buf * 64 + 16 * et + fr) * 72 + 32 * k2 + 4 * fq), v1 = *(const uint2*)(Vtm + (buf * 64 + 16 * et + fr) * 72 + 32 * k2 + 16 + 4 * fq);
;           const bf16x8 va = mk8(v0, v1);
; #pragma unroll
;           for (int qi = 0; qi < 2; ++qi) O[et][qi] = MFMA(va, pf[qi][k2], O[et][qi]);
;         }
.LBB0_1866:
	s_or_b64 exec, exec, s[18:19]
	s_mov_b32 s100, s34
	s_mov_b32 s101, s34
	v_max3_f32 v242, v96, s31, v97
	v_max3_f32 v243, v84, s31, v85
	v_max3_f32 v242, v242, v98, v99
	v_max3_f32 v243, v243, v86, v87
	v_max3_f32 v242, v242, v100, v101
	v_max3_f32 v243, v243, v88, v89
	v_max3_f32 v242, v242, v102, v103
	v_max3_f32 v243, v243, v90, v91
	v_max3_f32 v242, v242, v104, v105
	v_max3_f32 v243, v243, v80, v81
	v_max3_f32 v242, v242, v106, v107
	v_max3_f32 v243, v243, v82, v83
	v_max3_f32 v242, v242, v108, v109
	v_max3_f32 v243, v243, v92, v93
	v_max3_f32 v242, v242, v110, v111
	v_max3_f32 v243, v243, v94, v95
	v_mul_f32_e32 v242, 0x3e16c740, v242
	v_mul_f32_e32 v243, 0x3e16c740, v243
	v_mov_b32_e32 v244, v242
	v_mov_b32_e32 v245, v243
	s_nop 0
	v_permlane16_swap_b32_e32 v244, v242
	v_permlane16_swap_b32_e32 v245, v243
	v_max_f32_e32 v242, v242, v244
	v_max_f32_e32 v243, v243, v245
	v_mov_b32_e32 v244, v242
	v_mov_b32_e32 v245, v243
	s_nop 0
	v_permlane32_swap_b32_e32 v244, v242
	v_permlane32_swap_b32_e32 v245, v243
	v_max3_f32 v131, v154, v242, v244
	v_max3_f32 v209, v208, v243, v245
	v_sub_f32_e32 v242, v154, v131
	v_sub_f32_e32 v243, v208, v209
	v_sub_f32_e32 v246, 0, v131
	v_sub_f32_e32 v248, 0, v209
	v_pk_fma_f32 v[210:211], v[96:97], s[100:101], v[246:247] op_sel_hi:[1,1,0]
	v_pk_fma_f32 v[226:227], v[80:81], s[100:101], v[248:249] op_sel_hi:[1,1,0]
	v_pk_fma_f32 v[212:213], v[98:99], s[100:101], v[246:247] op_sel_hi:[1,1,0]
	v_pk_fma_f32 v[228:229], v[82:83], s[100:101], v[248:249] op_sel_hi:[1,1,0]
	v_pk_fma_f32 v[214:215], v[100:101], s[100:101], v[246:247] op_sel_hi:[1,1,0]
	v_pk_fma_f32 v[230:231], v[84:85], s[100:101], v[248:249] op_sel_hi:[1,1,0]
	v_pk_fma_f32 v[216:217], v[102:103], s[100:101], v[246:247] op_sel_hi:[1,1,0]
	v_pk_fma_f32 v[232:233], v[86:87], s[100:101], v[248:249] op_sel_hi:[1,1,0]
	v_pk_fma_f32 v[218:219], v[104:105], s[100:101], v[246:247] op_sel_hi:[1,1,0]
	v_pk_fma_f32 v[234:235], v[88:89], s[100:101], v[248:249] op_sel_hi:[1,1,0]
	v_pk_fma_f32 v[220:221], v[106:107], s[100:101], v[246:247] op_sel_hi:[1,1,0]
	v_pk_fma_f32 v[236:237], v[90:91], s[100:101], v[248:249] op_sel_hi:[1,1,0]
	v_pk_fma_f32 v[222:223], v[108:109], s[100:101], v[246:247] op_sel_hi:[1,1,0]
	v_pk_fma_f32 v[238:239], v[92:93], s[100:101], v[248:249] op_sel_hi:[1,1,0]
	v_pk_fma_f32 v[224:225], v[110:111], s[100:101], v[246:247] op_sel_hi:[1,1,0]
	v_pk_fma_f32 v[240:241], v[94:95], s[100:101], v[248:249] op_sel_hi:[1,1,0]
	v_exp_f32_e32 v178, v242
	v_exp_f32_e32 v90, v243
	v_exp_f32_e32 v163, v210
	v_exp_f32_e32 v170, v226
	v_exp_f32_e32 v165, v211
	v_exp_f32_e32 v104, v227
	v_exp_f32_e32 v167, v212
	v_exp_f32_e32 v172, v228
	v_exp_f32_e32 v169, v213
	v_exp_f32_e32 v106, v229
	v_exp_f32_e32 v155, v214
	v_exp_f32_e32 v162, v230
	v_exp_f32_e32 v157, v215
	v_exp_f32_e32 v164, v231
	v_exp_f32_e32 v159, v216
	v_exp_f32_e32 v166, v232
	v_exp_f32_e32 v161, v217
	v_exp_f32_e32 v168, v233
	v_exp_f32_e32 v171, v218
	v_exp_f32_e32 v154, v234
	v_exp_f32_e32 v105, v219
	v_exp_f32_e32 v156, v235
	v_exp_f32_e32 v173, v220
	v_exp_f32_e32 v158, v236
	v_exp_f32_e32 v107, v221
	v_exp_f32_e32 v160, v237
	v_exp_f32_e32 v175, v222
	v_exp_f32_e32 v174, v238
	v_exp_f32_e32 v109, v223
	v_exp_f32_e32 v108, v239
	v_exp_f32_e32 v177, v224
	v_exp_f32_e32 v176, v240
	v_exp_f32_e32 v111, v225
	v_exp_f32_e32 v110, v241
	v_add_u32_e32 v242, 0x6800, v203
	v_add_u32_e32 v243, 0x7000, v203
	v_add_u32_e32 v244, 0x7800, v203
	v_add_u32_e32 v245, 0x8000, v203
	ds_read2_b64 v[210:213], v242 offset1:4
	ds_read2_b64 v[214:217], v243 offset0:32 offset1:36
	ds_read2_b64 v[218:221], v244 offset0:64 offset1:68
	ds_read2_b64 v[222:225], v245 offset0:96 offset1:100
	ds_read2_b64 v[226:229], v243 offset0:40 offset1:44
	ds_read2_b64 v[230:233], v242 offset0:8 offset1:12
	ds_read2_b64 v[234:237], v244 offset0:72 offset1:76
	ds_read2_b64 v[238:241], v245 offset0:104 offset1:108
	v_pk_add_f32 v[80:81], v[154:155], 0 op_sel_hi:[1,0]
	v_pk_add_f32 v[80:81], v[156:157], v[80:81]
	v_pk_add_f32 v[80:81], v[158:159], v[80:81]
	v_pk_add_f32 v[80:81], v[160:161], v[80:81]
	v_pk_add_f32 v[80:81], v[162:163], v[80:81]
	v_pk_mul_f32 v[102:103], v[66:67], v[178:179] op_sel_hi:[1,0]
	v_pk_add_f32 v[80:81], v[164:165], v[80:81]
	v_pk_mul_f32 v[100:101], v[64:65], v[178:179] op_sel_hi:[1,0]
	v_pk_add_f32 v[80:81], v[166:167], v[80:81]
	v_pk_mul_f32 v[64:65], v[76:77], v[178:179] op_sel_hi:[1,0]
	v_pk_add_f32 v[80:81], v[168:169], v[80:81]
	v_cvt_pk_bf16_f32 v76, v171, v105
	v_pk_mul_f32 v[98:99], v[70:71], v[178:179] op_sel_hi:[1,0]
	v_pk_add_f32 v[80:81], v[170:171], v[80:81]
	v_pk_mul_f32 v[96:97], v[68:69], v[178:179] op_sel_hi:[1,0]
	v_pk_add_f32 v[88:89], v[104:105], v[80:81]
	v_cvt_pk_bf16_f32 v68, v155, v157
	v_cvt_pk_bf16_f32 v69, v159, v161
	v_pk_mul_f32 v[84:85], v[52:53], v[90:91] op_sel_hi:[1,0]
	v_pk_add_f32 v[52:53], v[172:173], v[88:89]
	v_pk_mul_f32 v[82:83], v[50:51], v[90:91] op_sel_hi:[1,0]
	v_pk_add_f32 v[52:53], v[106:107], v[52:53]
	v_pk_mul_f32 v[80:81], v[48:49], v[90:91] op_sel_hi:[1,0]
	v_pk_add_f32 v[52:53], v[174:175], v[52:53]
	v_pk_mul_f32 v[86:87], v[54:55], v[90:91] op_sel_hi:[1,0]
	v_pk_add_f32 v[52:53], v[108:109], v[52:53]
	v_pk_mul_f32 v[58:59], v[58:59], v[90:91] op_sel_hi:[1,0]
	v_pk_add_f32 v[52:53], v[176:177], v[52:53]
	v_pk_mul_f32 v[56:57], v[56:57], v[90:91] op_sel_hi:[1,0]
	v_pk_mul_f32 v[50:51], v[62:63], v[90:91] op_sel_hi:[1,0]
	v_pk_mul_f32 v[48:49], v[60:61], v[90:91] op_sel_hi:[1,0]
	v_mov_b32_e32 v91, v178
	v_pk_add_f32 v[52:53], v[110:111], v[52:53]
	v_cvt_pk_bf16_f32 v60, v170, v104
	v_pk_fma_f32 v[120:121], v[120:121], v[90:91], v[52:53]
	v_cvt_pk_bf16_f32 v70, v163, v165
	v_cvt_pk_bf16_f32 v71, v167, v169
	v_cvt_pk_bf16_f32 v52, v154, v156
	v_cvt_pk_bf16_f32 v53, v158, v160
	v_cvt_pk_bf16_f32 v54, v162, v164
	v_cvt_pk_bf16_f32 v55, v166, v168
	v_cvt_pk_bf16_f32 v61, v172, v106
	s_waitcnt lgkmcnt(7)
; DEVI bf16x8 mk8(uint2 a, uint2 b) { union { uint4 u; bf16x8 v; } c; c.u = make_uint4(a.x, a.y, b.x, b.y); return c.v; }
; #define MFMA(a, b, c) __builtin_amdgcn_mfma_f32_16x16x32_bf16((a), (b), (c), 0, 0, 0)
; template <int DK, bool BIAS> ...
;     ...
; #pragma unroll
;       for (int k2 = 0; k2 < 2; ++k2)
; #pragma unroll
;         for (int et = 0; et < 4; ++et) {
;           const uint2 v0 = *(const uint2*)(Vtm + (buf * 64 + 16 * et + fr) * 72 + 32 * k2 + 4 * fq), v1 = *(const uint2*)(Vtm + (buf * 64 + 16 * et + fr) * 72 + 32 * k2 + 16 + 4 * fq);
;           const bf16x8 va = mk8(v0, v1);
; #pragma unroll
;           for (int qi = 0; qi < 2; ++qi) O[et][qi] = MFMA(va, pf[qi][k2], O[et][qi]);
;         }
	v_mfma_f32_16x16x32_bf16 v[92:95], v[210:213], v[68:71], v[100:103]
	v_pk_mul_f32 v[74:75], v[74:75], v[178:179] op_sel_hi:[1,0]
	v_pk_mul_f32 v[72:73], v[72:73], v[178:179] op_sel_hi:[1,0]
	v_mfma_f32_16x16x32_bf16 v[80:83], v[210:213], v[52:55], v[80:83]
	v_cvt_pk_bf16_f32 v77, v173, v107
	s_waitcnt lgkmcnt(6)
	v_mfma_f32_16x16x32_bf16 v[96:99], v[214:217], v[68:71], v[96:99]
	v_pk_mul_f32 v[66:67], v[78:79], v[178:179] op_sel_hi:[1,0]
	v_cvt_pk_bf16_f32 v78, v175, v109
	v_cvt_pk_bf16_f32 v79, v177, v111
	v_mfma_f32_16x16x32_bf16 v[84:87], v[214:217], v[52:55], v[84:87]
	v_cvt_pk_bf16_f32 v62, v174, v108
	v_cvt_pk_bf16_f32 v63, v176, v110
	s_waitcnt lgkmcnt(5)
	v_mfma_f32_16x16x32_bf16 v[72:75], v[218:221], v[68:71], v[72:75]
	v_mov_b32_e32 v208, v209
	v_mov_b32_e32 v154, v131
	v_mfma_f32_16x16x32_bf16 v[56:59], v[218:221], v[52:55], v[56:59]
	s_waitcnt lgkmcnt(4)
	v_mfma_f32_16x16x32_bf16 v[100:103], v[222:225], v[68:71], v[64:67]
	v_mfma_f32_16x16x32_bf16 v[88:91], v[222:225], v[52:55], v[48:51]
	s_nop 1
	s_waitcnt lgkmcnt(2)
	v_mfma_f32_16x16x32_bf16 v[64:67], v[230:233], v[76:79], v[92:95]
	v_mfma_f32_16x16x32_bf16 v[48:51], v[230:233], v[60:63], v[80:83]
	s_nop 2
	s_waitcnt lgkmcnt(1)
	v_mfma_f32_16x16x32_bf16 v[72:75], v[234:237], v[76:79], v[72:75]
	v_mfma_f32_16x16x32_bf16 v[56:59], v[234:237], v[60:63], v[56:59]
	v_mfma_f32_16x16x32_bf16 v[68:71], v[226:229], v[76:79], v[96:99]
	v_mfma_f32_16x16x32_bf16 v[52:55], v[226:229], v[60:63], v[84:87]
	s_waitcnt lgkmcnt(0)
	v_mfma_f32_16x16x32_bf16 v[76:79], v[238:241], v[76:79], v[100:103]
	v_mfma_f32_16x16x32_bf16 v[60:63], v[238:241], v[60:63], v[88:91]

; DEVI unsigned pk_bf16(float lo, float hi) { unsigned r; asm("v_cvt_pk_bf16_f32 %0, %1, %2" : "=v"(r) : "v"(lo), "v"(hi)); return r; }
; DEVI bf16x8 mk8(uint2 a, uint2 b) { union { uint4 u; bf16x8 v; } c; c.u = make_uint4(a.x, a.y, b.x, b.y); return c.v; }
; template <int DK, bool BIAS> ...
;     ...
;       for (int qi = 0; qi < 2; ++qi) {
;         float mx = -3e38f;
;         if (BIAS) {
; #pragma unroll
;           for (int kt = 0; kt < 4; ++kt) { const f32x4 nf = *(const f32x4*)(fkm + buf * 64 + 16 * kt + 4 * fq);
; #pragma unroll
;             for (int r = 0; r < 4; ++r) { const float t = fmaf(S[kt][qi][r], sc2, nf[r]); S[kt][qi][r] = t; mx = fmaxf(mx, t); } }
;         } else {
; #pragma unroll
;           for (int kt = 0; kt < 4; ++kt)
; #pragma unroll
;             for (int r = 0; r < 4; ++r) mx = fmaxf(mx, S[kt][qi][r]);
;           mx *= sc2;
;         }
;         mx = fmaxf(mx, __shfl_xor(mx, 16)); mx = fmaxf(mx, __shfl_xor(mx, 32));
;         const float mold = mrun[qi], mnew = fmaxf(mold, mx);
;         mrun[qi] = mnew;
;         float ps = 0.f;
; #pragma unroll
;         for (int kt = 0; kt < 4; ++kt)
; #pragma unroll
;           for (int r = 0; r < 4; ++r) { const float pv = BIAS ? __builtin_amdgcn_exp2f(S[kt][qi][r] - mnew) : __builtin_amdgcn_exp2f(fmaf(S[kt][qi][r], sc2, -mnew)); S[kt][qi][r] = pv; ps += pv; }
;         {
;           const float alpha = __builtin_amdgcn_exp2f(mold - mnew);
;           lrun[qi] *= alpha;
; #pragma unroll
;           for (int et = 0; et < 4; ++et) O[et][qi] *= alpha;
;         }
;         lrun[qi] += ps;
; #pragma unroll
;         for (int k2 = 0; k2 < 2; ++k2) { uint2 lo, hi; lo.x = pk_bf16(S[2 * k2][qi][0], S[2 * k2][qi][1]); lo.y = pk_bf16(S[2 * k2][qi][2], S[2 * k2][qi][3]);
;           hi.x = pk_bf16(S[2 * k2 + 1][qi][0], S[2 * k2 + 1][qi][1]); hi.y = pk_bf16(S[2 * k2 + 1][qi][2], S[2 * k2 + 1][qi][3]); pf[qi][k2] = mk8(lo, hi); }
;       }
; #pragma unroll
;       for (int k2 = 0; k2 < 2; ++k2)
; #pragma unroll
;         for (int et = 0; et < 4; ++et) {
;           const uint2 v0 = *(const uint2*)(Vtm + (buf * 64 + 16 * et + fr) * 72 + 32 * k2 + 4 * fq), v1 = *(const uint2*)(Vtm + (buf * 64 + 16 * et + fr) * 72 + 32 * k2 + 16 + 4 * fq);
;           const bf16x8 va = mk8(v0, v1);
; #pragma unroll
;           for (int qi = 0; qi < 2; ++qi) O[et][qi] = MFMA(va, pf[qi][k2], O[et][qi]);
;         }
.LBB0_1888:
	s_or_b64 exec, exec, s[18:19]
	s_mov_b32 s100, s34
	s_mov_b32 s101, s34
	v_max3_f32 v242, v96, s31, v97
	v_max3_f32 v243, v84, s31, v85
	v_max3_f32 v242, v242, v98, v99
	v_max3_f32 v243, v243, v86, v87
	v_max3_f32 v242, v242, v100, v101
	v_max3_f32 v243, v243, v88, v89
	v_max3_f32 v242, v242, v102, v103
	v_max3_f32 v243, v243, v90, v91
	v_max3_f32 v242, v242, v104, v105
	v_max3_f32 v243, v243, v80, v81
	v_max3_f32 v242, v242, v106, v107
	v_max3_f32 v243, v243, v82, v83
	v_max3_f32 v242, v242, v108, v109
	v_max3_f32 v243, v243, v92, v93
	v_max3_f32 v242, v242, v110, v111
	v_max3_f32 v243, v243, v94, v95
	v_mul_f32_e32 v242, 0x3e16c740, v242
	v_mul_f32_e32 v243, 0x3e16c740, v243
	v_mov_b32_e32 v244, v242
	v_mov_b32_e32 v245, v243
	s_nop 0
	v_permlane16_swap_b32_e32 v244, v242
	v_permlane16_swap_b32_e32 v245, v243
	v_max_f32_e32 v242, v242, v244
	v_max_f32_e32 v243, v243, v245
	v_mov_b32_e32 v244, v242
	v_mov_b32_e32 v245, v243
	s_nop 0
	v_permlane32_swap_b32_e32 v244, v242
	v_permlane32_swap_b32_e32 v245, v243
	v_max3_f32 v131, v154, v242, v244
	v_max3_f32 v209, v208, v243, v245
	v_sub_f32_e32 v242, v154, v131
	v_sub_f32_e32 v243, v208, v209
	v_sub_f32_e32 v246, 0, v131
	v_sub_f32_e32 v248, 0, v209
	v_pk_fma_f32 v[210:211], v[96:97], s[100:101], v[246:247] op_sel_hi:[1,1,0]
	v_pk_fma_f32 v[226:227], v[80:81], s[100:101], v[248:249] op_sel_hi:[1,1,0]
	v_pk_fma_f32 v[212:213], v[98:99], s[100:101], v[246:247] op_sel_hi:[1,1,0]
	v_pk_fma_f32 v[228:229], v[82:83], s[100:101], v[248:249] op_sel_hi:[1,1,0]
	v_pk_fma_f32 v[214:215], v[100:101], s[100:101], v[246:247] op_sel_hi:[1,1,0]
	v_pk_fma_f32 v[230:231], v[84:85], s[100:101], v[248:249] op_sel_hi:[1,1,0]
	v_pk_fma_f32 v[216:217], v[102:103], s[100:101], v[246:247] op_sel_hi:[1,1,0]
	v_pk_fma_f32 v[232:233], v[86:87], s[100:101], v[248:249] op_sel_hi:[1,1,0]
	v_pk_fma_f32 v[218:219], v[104:105], s[100:101], v[246:247] op_sel_hi:[1,1,0]
	v_pk_fma_f32 v[234:235], v[88:89], s[100:101], v[248:249] op_sel_hi:[1,1,0]
	v_pk_fma_f32 v[220:221], v[106:107], s[100:101], v[246:247] op_sel_hi:[1,1,0]
	v_pk_fma_f32 v[236:237], v[90:91], s[100:101], v[248:249] op_sel_hi:[1,1,0]
	v_pk_fma_f32 v[222:223], v[108:109], s[100:101], v[246:247] op_sel_hi:[1,1,0]
	v_pk_fma_f32 v[238:239], v[92:93], s[100:101], v[248:249] op_sel_hi:[1,1,0]
	v_pk_fma_f32 v[224:225], v[110:111], s[100:101], v[246:247] op_sel_hi:[1,1,0]
	v_pk_fma_f32 v[240:241], v[94:95], s[100:101], v[248:249] op_sel_hi:[1,1,0]
	v_exp_f32_e32 v178, v242
	v_exp_f32_e32 v90, v243
	v_exp_f32_e32 v163, v210
	v_exp_f32_e32 v162, v226
	v_exp_f32_e32 v165, v211
	v_exp_f32_e32 v164, v227
	v_exp_f32_e32 v167, v212
	v_exp_f32_e32 v166, v228
	v_exp_f32_e32 v169, v213
	v_exp_f32_e32 v168, v229
	v_exp_f32_e32 v155, v214
	v_exp_f32_e32 v170, v230
	v_exp_f32_e32 v157, v215
	v_exp_f32_e32 v104, v231
	v_exp_f32_e32 v159, v216
	v_exp_f32_e32 v172, v232
	v_exp_f32_e32 v161, v217
	v_exp_f32_e32 v106, v233
	v_exp_f32_e32 v171, v218
	v_exp_f32_e32 v154, v234
	v_exp_f32_e32 v105, v219
	v_exp_f32_e32 v156, v235
	v_exp_f32_e32 v173, v220
	v_exp_f32_e32 v158, v236
	v_exp_f32_e32 v107, v221
	v_exp_f32_e32 v160, v237
	v_exp_f32_e32 v175, v222
	v_exp_f32_e32 v174, v238
	v_exp_f32_e32 v109, v223
	v_exp_f32_e32 v108, v239
	v_exp_f32_e32 v177, v224
	v_exp_f32_e32 v176, v240
	v_exp_f32_e32 v111, v225
	v_exp_f32_e32 v110, v241
	v_add_u32_e32 v242, 0x6800, v206
	v_add_u32_e32 v243, 0x9000, v203
	v_add_u32_e32 v244, 0x9800, v203
	v_add_u32_e32 v245, 0xa000, v203
	ds_read2_b64 v[210:213], v242 offset1:4
	ds_read2_b64 v[214:217], v243 offset0:160 offset1:164
	ds_read2_b64 v[218:221], v244 offset0:192 offset1:196
	ds_read2_b64 v[222:225], v245 offset0:224 offset1:228
	ds_read2_b64 v[226:229], v243 offset0:168 offset1:172
	ds_read2_b64 v[230:233], v242 offset0:8 offset1:12
	ds_read2_b64 v[234:237], v244 offset0:200 offset1:204
	ds_read2_b64 v[238:241], v245 offset0:232 offset1:236
	v_pk_add_f32 v[80:81], v[154:155], 0 op_sel_hi:[1,0]
	v_pk_add_f32 v[80:81], v[156:157], v[80:81]
	v_pk_mul_f32 v[102:103], v[66:67], v[178:179] op_sel_hi:[1,0]
	v_pk_add_f32 v[80:81], v[158:159], v[80:81]
	v_pk_mul_f32 v[100:101], v[64:65], v[178:179] op_sel_hi:[1,0]
	v_pk_add_f32 v[80:81], v[160:161], v[80:81]
	v_pk_mul_f32 v[64:65], v[76:77], v[178:179] op_sel_hi:[1,0]
	v_pk_add_f32 v[80:81], v[162:163], v[80:81]
	v_cvt_pk_bf16_f32 v76, v171, v105
	v_pk_mul_f32 v[98:99], v[70:71], v[178:179] op_sel_hi:[1,0]
	v_pk_add_f32 v[80:81], v[164:165], v[80:81]
	v_pk_mul_f32 v[96:97], v[68:69], v[178:179] op_sel_hi:[1,0]
	v_pk_add_f32 v[88:89], v[166:167], v[80:81]
	v_cvt_pk_bf16_f32 v68, v155, v157
	v_cvt_pk_bf16_f32 v69, v159, v161
	v_cvt_pk_bf16_f32 v70, v163, v165
	v_cvt_pk_bf16_f32 v71, v167, v169
	v_pk_mul_f32 v[74:75], v[74:75], v[178:179] op_sel_hi:[1,0]
	v_pk_mul_f32 v[84:85], v[52:53], v[90:91] op_sel_hi:[1,0]
	v_pk_add_f32 v[52:53], v[168:169], v[88:89]
	v_pk_mul_f32 v[82:83], v[50:51], v[90:91] op_sel_hi:[1,0]
	v_pk_add_f32 v[52:53], v[170:171], v[52:53]
	v_pk_mul_f32 v[80:81], v[48:49], v[90:91] op_sel_hi:[1,0]
	v_pk_add_f32 v[52:53], v[104:105], v[52:53]
	v_pk_mul_f32 v[86:87], v[54:55], v[90:91] op_sel_hi:[1,0]
	v_pk_add_f32 v[52:53], v[172:173], v[52:53]
	v_pk_mul_f32 v[58:59], v[58:59], v[90:91] op_sel_hi:[1,0]
	v_pk_add_f32 v[52:53], v[106:107], v[52:53]
	v_pk_mul_f32 v[56:57], v[56:57], v[90:91] op_sel_hi:[1,0]
	v_pk_add_f32 v[52:53], v[174:175], v[52:53]
	v_pk_mul_f32 v[50:51], v[62:63], v[90:91] op_sel_hi:[1,0]
	v_pk_add_f32 v[52:53], v[108:109], v[52:53]
	v_pk_mul_f32 v[48:49], v[60:61], v[90:91] op_sel_hi:[1,0]
	v_pk_add_f32 v[52:53], v[176:177], v[52:53]
	v_mov_b32_e32 v91, v178
	v_pk_add_f32 v[52:53], v[110:111], v[52:53]
	v_cvt_pk_bf16_f32 v60, v170, v104
	v_pk_fma_f32 v[120:121], v[120:121], v[90:91], v[52:53]
	v_cvt_pk_bf16_f32 v52, v154, v156
	v_cvt_pk_bf16_f32 v53, v158, v160
	v_cvt_pk_bf16_f32 v54, v162, v164
	v_cvt_pk_bf16_f32 v55, v166, v168
	s_waitcnt lgkmcnt(7)
; DEVI bf16x8 mk8(uint2 a, uint2 b) { union { uint4 u; bf16x8 v; } c; c.u = make_uint4(a.x, a.y, b.x, b.y); return c.v; }
; #define MFMA(a, b, c) __builtin_amdgcn_mfma_f32_16x16x32_bf16((a), (b), (c), 0, 0, 0)
; template <int DK, bool BIAS> ...
;     ...
; #pragma unroll
;       for (int k2 = 0; k2 < 2; ++k2)
; #pragma unroll
;         for (int et = 0; et < 4; ++et) {
;           const uint2 v0 = *(const uint2*)(Vtm + (buf * 64 + 16 * et + fr) * 72 + 32 * k2 + 4 * fq), v1 = *(const uint2*)(Vtm + (buf * 64 + 16 * et + fr) * 72 + 32 * k2 + 16 + 4 * fq);
;           const bf16x8 va = mk8(v0, v1);
; #pragma unroll
;           for (int qi = 0; qi < 2; ++qi) O[et][qi] = MFMA(va, pf[qi][k2], O[et][qi]);
;         }
	v_mfma_f32_16x16x32_bf16 v[92:95], v[210:213], v[68:71], v[100:103]
	v_cvt_pk_bf16_f32 v61, v172, v106
	v_pk_mul_f32 v[72:73], v[72:73], v[178:179] op_sel_hi:[1,0]
	v_mfma_f32_16x16x32_bf16 v[80:83], v[210:213], v[52:55], v[80:83]
	v_cvt_pk_bf16_f32 v77, v173, v107
	s_waitcnt lgkmcnt(6)
	v_mfma_f32_16x16x32_bf16 v[96:99], v[214:217], v[68:71], v[96:99]
	v_pk_mul_f32 v[66:67], v[78:79], v[178:179] op_sel_hi:[1,0]
	v_cvt_pk_bf16_f32 v78, v175, v109
	v_cvt_pk_bf16_f32 v79, v177, v111
	v_mfma_f32_16x16x32_bf16 v[84:87], v[214:217], v[52:55], v[84:87]
	v_cvt_pk_bf16_f32 v62, v174, v108
	v_cvt_pk_bf16_f32 v63, v176, v110
	s_waitcnt lgkmcnt(5)
	v_mfma_f32_16x16x32_bf16 v[72:75], v[218:221], v[68:71], v[72:75]
	v_mov_b32_e32 v208, v209
	v_mov_b32_e32 v154, v131
	v_mfma_f32_16x16x32_bf16 v[56:59], v[218:221], v[52:55], v[56:59]
	s_waitcnt lgkmcnt(4)
	v_mfma_f32_16x16x32_bf16 v[100:103], v[222:225], v[68:71], v[64:67]
	v_mfma_f32_16x16x32_bf16 v[88:91], v[222:225], v[52:55], v[48:51]
	s_nop 1
	s_waitcnt lgkmcnt(2)
	v_mfma_f32_16x16x32_bf16 v[64:67], v[230:233], v[76:79], v[92:95]
	v_mfma_f32_16x16x32_bf16 v[48:51], v[230:233], v[60:63], v[80:83]
	s_nop 2
	s_waitcnt lgkmcnt(1)
	v_mfma_f32_16x16x32_bf16 v[72:75], v[234:237], v[76:79], v[72:75]
	v_mfma_f32_16x16x32_bf16 v[56:59], v[234:237], v[60:63], v[56:59]
	v_mfma_f32_16x16x32_bf16 v[68:71], v[226:229], v[76:79], v[96:99]
	v_mfma_f32_16x16x32_bf16 v[52:55], v[226:229], v[60:63], v[84:87]
	s_waitcnt lgkmcnt(0)
	v_mfma_f32_16x16x32_bf16 v[76:79], v[238:241], v[76:79], v[100:103]
	v_mfma_f32_16x16x32_bf16 v[60:63], v[238:241], v[60:63], v[88:91]
